# SEAM 1 as a split barrier hidden behind the weight transposes P2 does not need (w_in transposes -> pre-norm -> count-in -> other transposes -> poll)
# speedup vs baseline: 1.0269x; 1.0269x over previous
_Z14fwd_megakernel4Args:
	s_mov_b32 s100, 0
	s_load_dwordx8 s[84:91], s[0:1], 0xc0
	s_load_dwordx4 s[92:95], s[0:1], 0xe0
	s_load_dword s3, s[0:1], 0xf0
	s_add_u32 s4, s0, 0xf0
	s_addc_u32 s5, s1, 0
	v_readfirstlane_b32 s97, v0
	v_writelane_b32 v246, s4, 0
	v_cmp_gt_u32_e32 vcc, 2, v0
	s_nop 0
	v_writelane_b32 v246, s5, 1
	s_and_saveexec_b64 s[4:5], vcc
	v_lshl_add_u32 v1, v0, 2, 0
	v_add_u32_e32 v1, 0x22000, v1
	v_mov_b32_e32 v2, 0
	ds_write_b32 v1, v2
	s_or_b64 exec, exec, s[4:5]
	s_waitcnt lgkmcnt(0)
	s_barrier
	s_getreg_b32 s4, hwreg(HW_REG_XCC_ID, 0, 4)
	s_and_b32 s33, s4, 15
	v_cmp_eq_u32_e64 s[6:7], 0, v0
	s_mov_b64 s[4:5], exec
	s_nop 0
	v_writelane_b32 v246, s6, 2
	s_nop 1
	v_writelane_b32 v246, s7, 3
	s_and_b64 s[6:7], s[4:5], s[6:7]
	s_mov_b64 exec, s[6:7]
	s_cbranch_execz .LBB0_5
	s_mov_b64 s[6:7], exec
	v_mbcnt_lo_u32_b32 v1, s6, 0
	v_mbcnt_hi_u32_b32 v1, s7, v1
	v_cmp_eq_u32_e32 vcc, 0, v1
	s_and_b64 s[8:9], exec, vcc
	s_mov_b64 exec, s[8:9]
	s_cbranch_execz .LBB0_5
	s_lshl_b32 s8, s33, 8
	s_bcnt1_i32_b64 s6, s[6:7]
	v_mov_b32_e32 v1, s8
	v_mov_b32_e32 v2, s6
	global_atomic_add v1, v2, s[92:93] offset:1024
	s_and_b32 s8, s2, 15
	s_lshl_b32 s8, s8, 2
	s_add_u32 s8, s8, 0x54200
	s_add_u32 s10, s92, s8
	s_addc_u32 s11, s93, 0
	s_lshl_b32 s9, 1, s33
	v_mov_b32_e32 v3, 0
	v_mov_b32_e32 v4, s9
	global_atomic_or v3, v4, s[10:11]

.LBB0_13:
	s_cmpk_gt_i32 s4, 0x21ff
	s_cbranch_scc1 .LBB0_36
	v_lshlrev_b32_e32 v2, 4, v0
	v_and_b32_e32 v26, 0x70, v2
	v_lshlrev_b32_e32 v2, 3, v0
	v_and_b32_e32 v2, 56, v2
	v_mul_u32_u24_e32 v6, 0x84, v2
	v_lshlrev_b32_e32 v2, 1, v2
	v_mov_b32_e32 v3, 0
	s_lshl_b32 s0, s96, 14
	v_lshrrev_b32_e32 v28, 3, v1
	v_lshl_add_u64 v[14:15], s[92:93], 0, v[2:3]
	s_mov_b64 s[8:9], 0x600000
	s_add_i32 s0, s0, 0
	v_lshl_add_u64 v[4:5], v[14:15], 0, s[8:9]
	v_lshlrev_b32_e32 v2, 2, v28
	s_mov_b64 s[8:9], 0xe00000
	v_add3_u32 v36, s0, v6, v2
	v_lshl_add_u64 v[6:7], v[14:15], 0, s[8:9]
	s_mov_b64 s[8:9], 0x2600000
	v_lshl_add_u64 v[8:9], v[14:15], 0, s[8:9]
	s_mov_b64 s[8:9], 0x2200800
	v_add_u32_e32 v37, s0, v26
	v_mul_u32_u24_e32 v38, 0x84, v28
	v_lshl_add_u64 v[10:11], v[14:15], 0, s[8:9]
	s_mov_b64 s[8:9], 0x2200000
	v_lshl_add_u64 v[12:13], v[14:15], 0, s[8:9]
	s_mov_b64 s[8:9], 0x1600000
	v_mov_b32_e32 v27, v3
	s_lshl_b32 s0, s4, 1
	v_add_u32_e32 v37, v37, v38
	s_mov_b32 s1, 0
	v_or_b32_e32 v29, 8, v28
	v_or_b32_e32 v30, 16, v28
	v_or_b32_e32 v31, 24, v28
	v_or_b32_e32 v32, 32, v28
	v_or_b32_e32 v33, 40, v28
	v_or_b32_e32 v34, 48, v28
	v_or_b32_e32 v35, 56, v28
	v_lshl_add_u64 v[14:15], v[14:15], 0, s[8:9]
	v_lshl_add_u64 v[16:17], s[88:89], 0, v[26:27]
	v_lshl_add_u64 v[18:19], s[86:87], 0, v[26:27]
	v_lshl_add_u64 v[20:21], s[84:85], 0, v[26:27]
	s_waitcnt lgkmcnt(0)
	v_lshl_add_u64 v[22:23], s[26:27], 0, v[26:27]
	v_lshl_add_u64 v[24:25], s[24:25], 0, v[26:27]
	v_lshl_add_u64 v[26:27], s[58:59], 0, v[26:27]
	s_lshl_b32 s7, s4, 5
	s_lshl_b32 s10, s6, 5
	s_add_i32 s11, s0, 0x1cc00
	s_lshl_b32 s24, s6, 1
	v_add_u32_e32 v38, 0x420, v37
	v_add_u32_e32 v39, 0x428, v37
	v_add_u32_e32 v40, 0x840, v37
	v_add_u32_e32 v41, 0x848, v37
	v_add_u32_e32 v42, 0xc60, v37
	v_add_u32_e32 v43, 0xc68, v37
	v_add_u32_e32 v44, 0x1080, v37
	v_add_u32_e32 v45, 0x1088, v37
	v_add_u32_e32 v46, 0x14a0, v37
	v_add_u32_e32 v47, 0x14a8, v37
	v_add_u32_e32 v48, 0x18c0, v37
	v_add_u32_e32 v49, 0x18c8, v37
	v_add_u32_e32 v50, 0x1ce0, v37
	v_add_u32_e32 v51, 0x1ce8, v37
	s_movk_i32 s25, 0x6000
	s_mov_b32 s26, s4
	s_cmp_eq_u32 s100, 0
	s_cbranch_scc1 .LBB0_16
	s_mov_b32 s26, s101
	s_lshl_b32 s7, s26, 5
	s_lshl_b32 s11, s26, 1
	s_add_i32 s11, s11, 0x1cc00
	s_branch .LBB0_16
.LBB0_15:
	s_add_i32 s26, s26, s6
	s_add_i32 s7, s7, s10
	s_add_i32 s11, s11, s24
	s_cmp_lg_u32 s100, 0
	s_cbranch_scc1 .Lp0_pass2
	s_cmpk_lt_i32 s26, 0xc00
	s_cbranch_scc1 .LBB0_16
	s_mov_b32 s101, s26
	s_branch .LBB0_36
.Lp0_pass2:
	s_cmpk_lt_i32 s26, 0x2000
	s_cbranch_scc1 .LBB0_16
	s_add_i32 s99, s4, 0x2000
	s_cmp_lg_u32 s26, s99
	s_cbranch_scc1 .LBB0_36
	s_cmpk_lt_u32 s4, 0x600
	s_cbranch_scc1 .LBB0_36
	s_add_i32 s26, s4, 0x1a00
	s_lshl_b32 s7, s26, 5
	s_lshl_b32 s11, s26, 1
	s_add_i32 s11, s11, 0x1cc00

.LBB0_36:
	s_cmp_eq_u32 s100, 0
	s_cbranch_scc1 .LBB0_47
	s_cmpk_lt_u32 s3, 0xc1
	s_cselect_b64 s[0:1], -1, 0
	s_cmpk_gt_u32 s2, 0xbf
	s_cselect_b64 s[8:9], -1, 0
	s_or_b64 s[8:9], s[0:1], s[8:9]
	s_and_b64 vcc, exec, s[8:9]
	s_cbranch_vccz .LBB0_47
	s_lshl_b32 s8, s2, 9
	s_add_i32 s5, s8, s5
	s_lshl_b32 s8, s3, 9
	s_lshl_b32 s7, s4, 6
	s_add_i32 s5, s5, 0xfffe8000
	s_add_i32 s9, s8, 0xfffe8000
	s_and_b64 s[0:1], s[0:1], exec
	s_cselect_b32 s0, s7, s5
	v_or_b32_e32 v6, s0, v1
	s_mov_b32 s0, 0x8000
	s_cselect_b32 s8, s8, s9
	v_cmp_gt_i32_e32 vcc, s0, v6
	v_ashrrev_i32_e32 v7, 31, v6
	s_and_saveexec_b64 s[0:1], vcc
	s_cbranch_execz .LBB0_40
	v_and_b32_e32 v2, 15, v0
	v_mov_b32_e32 v3, 0
	v_lshl_add_u64 v[4:5], v[6:7], 4, s[92:93]
	s_mov_b64 s[10:11], 0x500000
	s_ashr_i32 s9, s8, 31
	v_lshl_add_u64 v[4:5], v[4:5], 0, s[10:11]
	s_lshl_b64 s[10:11], s[8:9], 4
	s_waitcnt lgkmcnt(0)
	s_mov_b64 s[24:25], 0
	v_mov_b32_e32 v10, s19
	v_mov_b32_e32 v11, s15
	v_mov_b32_e32 v12, s18
	v_mov_b32_e32 v13, s14
	v_lshlrev_b32_e32 v8, 2, v2
	v_mov_b32_e32 v9, v3
	s_mov_b32 s14, 0xbfb8aa3b
	s_movk_i32 s5, 0x7fff
	v_mov_b32_e32 v14, v6
.LBB0_39:
	v_lshrrev_b32_e32 v16, 5, v14
	v_ashrrev_i32_e32 v15, 11, v14
	v_and_b32_e32 v2, 0x400, v14
	v_lshrrev_b32_e32 v18, 1, v14
	v_and_b32_e32 v19, 16, v16
	v_cmp_eq_u32_e32 vcc, 0, v2
	v_and_b32_e32 v20, 32, v18
	v_and_b32_e32 v21, 24, v18
	v_and_b32_e32 v2, 0xc0, v18
	v_add_u32_e32 v18, v19, v15
	v_ashrrev_i32_e32 v19, 31, v18
	v_lshlrev_b64 v[18:19], 6, v[18:19]
	v_or3_b32 v18, v18, v20, v21
	v_cndmask_b32_e32 v17, v10, v11, vcc
	v_cndmask_b32_e32 v16, v12, v13, vcc
	v_lshlrev_b64 v[18:19], 8, v[18:19]
	v_lshl_add_u64 v[16:17], v[16:17], 0, v[18:19]
	v_lshl_add_u64 v[16:17], v[16:17], 0, v[2:3]
	v_lshl_add_u64 v[16:17], v[16:17], 0, v[8:9]
	global_load_dword v18, v[16:17], off
	global_load_dword v19, v[16:17], off offset:256
	global_load_dword v20, v[16:17], off offset:512
	global_load_dword v21, v[16:17], off offset:768
	global_load_dword v22, v[16:17], off offset:1024
	global_load_dword v23, v[16:17], off offset:1280
	global_load_dword v24, v[16:17], off offset:1536
	global_load_dword v25, v[16:17], off offset:1792
	v_add_u32_e32 v14, s8, v14
	v_cmp_lt_i32_e32 vcc, s5, v14
	s_or_b64 s[24:25], vcc, s[24:25]
	s_waitcnt vmcnt(6)
	v_pk_mul_f32 v[16:17], v[18:19], s[14:15] op_sel_hi:[1,0]
	s_nop 0
	v_cvt_pk_bf16_f32 v16, v16, v17
	s_waitcnt vmcnt(4)
	v_pk_mul_f32 v[18:19], v[20:21], s[14:15] op_sel_hi:[1,0]
	s_waitcnt vmcnt(2)
	v_pk_mul_f32 v[20:21], v[22:23], s[14:15] op_sel_hi:[1,0]
	v_cvt_pk_bf16_f32 v17, v18, v19
	s_waitcnt vmcnt(0)
	v_pk_mul_f32 v[22:23], v[24:25], s[14:15] op_sel_hi:[1,0]
	v_cvt_pk_bf16_f32 v18, v20, v21
	v_cvt_pk_bf16_f32 v19, v22, v23
	global_store_dwordx4 v[4:5], v[16:19], off sc1
	v_lshl_add_u64 v[4:5], v[4:5], 0, s[10:11]
	s_andn2_b64 exec, exec, s[24:25]
	s_cbranch_execnz .LBB0_39

.LBB0_42:
	global_load_dwordx4 v[10:13], v[2:3], off offset:-16
	global_load_dwordx4 v[14:17], v[2:3], off
	v_add_u32_e32 v8, s8, v8
	v_cmp_lt_i32_e32 vcc, s5, v8
	v_lshl_add_u64 v[2:3], v[2:3], 0, s[10:11]
	s_or_b64 s[18:19], vcc, s[18:19]
	s_waitcnt vmcnt(1)
	v_cvt_pk_bf16_f32 v10, v10, v11
	v_cvt_pk_bf16_f32 v11, v12, v13
	s_waitcnt vmcnt(0)
	v_cvt_pk_bf16_f32 v12, v14, v15
	v_cvt_pk_bf16_f32 v13, v16, v17
	global_store_dwordx4 v[4:5], v[10:13], off sc1
	v_lshl_add_u64 v[4:5], v[4:5], 0, s[14:15]
	s_andn2_b64 exec, exec, s[18:19]
	s_cbranch_execnz .LBB0_42

.LBB0_45:
	v_lshl_add_u64 v[2:3], s[22:23], 0, v[8:9]
	v_lshl_add_u64 v[18:19], s[16:17], 0, v[8:9]
	v_lshl_add_u64 v[20:21], s[20:21], 0, v[8:9]
	global_load_dword v4, v[2:3], off
	s_nop 0
	global_load_dword v2, v[18:19], off
	global_load_dword v3, v[20:21], off
	v_add_u32_e32 v6, s8, v6
	v_cmp_lt_i32_e32 vcc, s31, v6
	s_or_b64 s[24:25], vcc, s[24:25]
	v_lshl_add_u64 v[8:9], v[8:9], 0, s[14:15]
	s_waitcnt vmcnt(2)
	v_mul_f32_e32 v13, 0xbfb8aa3b, v4
	v_fma_f32 v19, v4, s5, -v13
	v_rndne_f32_e32 v20, v13
	v_fmac_f32_e32 v19, 0xb2a5705f, v4
	v_sub_f32_e32 v13, v13, v20
	v_add_f32_e32 v13, v13, v19
	s_waitcnt vmcnt(1)
	v_mul_f32_e32 v17, 0xbfb8aa3b, v2
	s_waitcnt vmcnt(0)
	v_mul_f32_e32 v18, 0xbfb8aa3b, v3
	v_cvt_i32_f32_e32 v20, v20
	v_exp_f32_e32 v13, v13
	v_cmp_gt_f32_e32 vcc, s30, v17
	v_cmp_gt_f32_e64 s[0:1], s30, v18
	v_ldexp_f32 v13, v13, v20
	v_cndmask_b32_e32 v17, 0, v15, vcc
	v_cndmask_b32_e64 v18, 0, v15, s[0:1]
	v_fmac_f32_e32 v17, 0xbfb8aa3b, v2
	v_fmac_f32_e32 v18, 0xbfb8aa3b, v3
	v_cndmask_b32_e32 v2, 0, v16, vcc
	v_exp_f32_e32 v17, v17
	v_exp_f32_e32 v18, v18
	v_cmp_nlt_f32_e32 vcc, s7, v4
	v_cndmask_b32_e64 v3, 0, v16, s[0:1]
	v_ldexp_f32 v2, v17, v2
	v_cndmask_b32_e32 v13, 0, v13, vcc
	v_cmp_ngt_f32_e32 vcc, s9, v4
	v_ldexp_f32 v3, v18, v3
	s_nop 0
	v_cndmask_b32_e32 v4, v7, v13, vcc
	v_add_f32_e32 v13, 1.0, v4
	v_add_f32_e32 v17, -1.0, v13
	v_frexp_mant_f32_e32 v20, v13
	v_cvt_f64_f32_e32 v[18:19], v13
	v_sub_f32_e32 v21, v17, v13
	v_frexp_exp_i32_f64_e32 v18, v[18:19]
	v_cmp_gt_f32_e32 vcc, s27, v20
	v_sub_f32_e32 v17, v4, v17
	v_add_f32_e32 v19, 1.0, v21
	v_subbrev_co_u32_e32 v18, vcc, 0, v18, vcc
	v_add_f32_e32 v17, v17, v19
	v_sub_u32_e32 v19, 0, v18
	v_ldexp_f32 v13, v13, v19
	v_ldexp_f32 v17, v17, v19
	v_add_f32_e32 v19, -1.0, v13
	v_add_f32_e32 v20, 1.0, v13
	v_add_f32_e32 v21, 1.0, v19
	v_add_f32_e32 v22, -1.0, v20
	v_sub_f32_e32 v21, v13, v21
	v_sub_f32_e32 v13, v13, v22
	v_add_f32_e32 v13, v17, v13
	v_add_f32_e32 v22, v17, v21
	v_add_f32_e32 v17, v20, v13
	v_rcp_f32_e32 v26, v17
	v_add_f32_e32 v21, v19, v22
	v_sub_f32_e32 v19, v19, v21
	v_sub_f32_e32 v20, v20, v17
	v_mul_f32_e32 v27, v21, v26
	v_add_f32_e32 v19, v22, v19
	v_mul_f32_e32 v22, v17, v27
	v_add_f32_e32 v13, v13, v20
	v_fma_f32 v24, v27, v17, -v22
	v_fmac_f32_e32 v24, v27, v13
	v_add_f32_e32 v20, v22, v24
	v_sub_f32_e32 v23, v21, v20
	v_mov_b32_e32 v25, v20
	v_pk_add_f32 v[20:21], v[20:21], v[22:23] neg_lo:[0,1] neg_hi:[0,1]
	v_cvt_f32_i32_e32 v18, v18
	v_pk_add_f32 v[20:21], v[20:21], v[24:25] neg_lo:[0,1] neg_hi:[0,1]
	v_cmp_neq_f32_e32 vcc, s26, v4
	v_add_f32_e32 v19, v19, v21
	v_add_f32_e32 v19, v20, v19
	v_add_f32_e32 v21, v23, v19
	v_mul_f32_e32 v20, v26, v21
	v_mul_f32_e32 v22, v17, v20
	v_add_f32_e32 v28, v27, v20
	v_fma_f32 v24, v20, v17, -v22
	v_sub_f32_e32 v17, v28, v27
	v_fmac_f32_e32 v24, v20, v13
	v_sub_f32_e32 v23, v23, v21
	v_sub_f32_e32 v13, v20, v17
	v_add_f32_e32 v20, v22, v24
	v_add_f32_e32 v19, v19, v23
	v_sub_f32_e32 v23, v21, v20
	v_mov_b32_e32 v25, v20
	v_pk_add_f32 v[20:21], v[20:21], v[22:23] neg_lo:[0,1] neg_hi:[0,1]
	s_nop 0
	v_pk_add_f32 v[20:21], v[20:21], v[24:25] neg_lo:[0,1] neg_hi:[0,1]
	s_nop 0
	v_add_f32_e32 v17, v19, v21
	v_add_f32_e32 v17, v20, v17
	v_add_f32_e32 v17, v23, v17
	v_mul_f32_e32 v17, v26, v17
	v_add_f32_e32 v13, v13, v17
	v_add_f32_e32 v17, v28, v13
	v_mul_f32_e32 v20, v17, v17
	v_sub_f32_e32 v19, v17, v28
	v_fmamk_f32 v22, v20, 0x3e9b6dac, v14
	v_sub_f32_e32 v23, v13, v19
	v_mul_f32_e32 v19, v17, v20
	v_fmaak_f32 v13, v20, v22, 0x3f2aaada
	v_ldexp_f32 v21, v17, 1
	v_ldexp_f32 v17, v23, 1
	v_pk_mul_f32 v[22:23], v[18:19], v[12:13]
	s_nop 0
	v_fma_f32 v20, v18, s28, -v22
	v_fmac_f32_e32 v20, 0xb102e308, v18
	v_pk_add_f32 v[18:19], v[22:23], v[20:21]
	v_mov_b32_e32 v24, v22
	v_sub_f32_e32 v13, v19, v21
	v_sub_f32_e32 v13, v23, v13
	v_add_f32_e32 v25, v17, v13
	v_pk_add_f32 v[26:27], v[18:19], v[22:23] neg_lo:[0,1] neg_hi:[0,1]
	v_pk_add_f32 v[22:23], v[18:19], v[24:25]
	v_mov_b32_e32 v21, v18
	v_mov_b32_e32 v27, v23
	v_pk_add_f32 v[30:31], v[20:21], v[26:27] neg_lo:[0,1] neg_hi:[0,1]
	v_pk_add_f32 v[20:21], v[20:21], v[26:27]
	v_mov_b32_e32 v29, v18
	v_pk_add_f32 v[26:27], v[20:21], v[18:19] op_sel:[1,0] op_sel_hi:[0,1] neg_lo:[0,1] neg_hi:[0,1]
	v_mov_b32_e32 v28, v25
	v_mov_b32_e32 v24, v23
	v_mov_b32_e32 v25, v21
	v_pk_mov_b32 v[18:19], v[18:19], v[26:27] op_sel:[1,0]
	v_pk_add_f32 v[22:23], v[22:23], v[26:27] op_sel_hi:[1,0] neg_lo:[0,1] neg_hi:[0,1]
	v_pk_add_f32 v[18:19], v[24:25], v[18:19] neg_lo:[0,1] neg_hi:[0,1]
	v_mov_b32_e32 v22, v30
	v_pk_add_f32 v[18:19], v[28:29], v[18:19] neg_lo:[0,1] neg_hi:[0,1]
	v_mov_b32_e32 v31, v21
	v_pk_add_f32 v[22:23], v[22:23], v[18:19]
	s_nop 0
	v_pk_add_f32 v[24:25], v[22:23], v[22:23] op_sel:[0,1] op_sel_hi:[1,0]
	s_nop 0
	v_pk_add_f32 v[20:21], v[20:21], v[24:25] op_sel:[1,0] op_sel_hi:[0,1]
	v_mov_b32_e32 v23, v20
	v_mov_b32_e32 v19, v24
	v_pk_add_f32 v[24:25], v[22:23], v[30:31] neg_lo:[0,1] neg_hi:[0,1]
	s_nop 0
	v_sub_f32_e32 v13, v22, v24
	v_pk_add_f32 v[18:19], v[18:19], v[24:25] neg_lo:[0,1] neg_hi:[0,1]
	v_sub_f32_e32 v13, v30, v13
	v_add_f32_e32 v13, v18, v13
	v_add_f32_e32 v13, v13, v19
	v_add_f32_e32 v13, v20, v13
	v_cndmask_b32_e32 v13, v7, v13, vcc
	v_cmp_lt_f32_e64 vcc, |v4|, s29
	s_nop 1
	v_cndmask_b32_e32 v4, v13, v4, vcc
	v_mul_f32_e32 v4, 0xc1000000, v4
	v_mul_f32_e32 v4, 0x3fb8aa3b, v4
	global_store_dwordx4 v[10:11], v[2:5], off sc1
	v_lshl_add_u64 v[10:11], v[10:11], 0, s[18:19]
	s_andn2_b64 exec, exec, s[24:25]
	s_cbranch_execnz .LBB0_45

.LBB0_47:
	s_cmp_lg_u32 s100, 0
	s_cbranch_scc1 .Lsb1_wait
	s_cmp_lt_i32 s94, 2
	s_cselect_b64 s[0:1], -1, 0
	s_cmp_gt_i32 s95, 1
	s_cselect_b64 s[8:9], -1, 0
	s_and_b64 s[0:1], s[0:1], s[8:9]
	s_andn2_b64 vcc, exec, s[0:1]
	s_cbranch_vccnz .LBB0_70
	s_mov_b64 s[8:9], exec
	v_readlane_b32 s10, v246, 2
	v_readlane_b32 s11, v246, 3
	s_and_b64 s[10:11], s[8:9], s[10:11]
	s_mov_b64 exec, s[10:11]
	s_cbranch_execz .LBB0_58
	s_min_i32 s5, s3, 0xc0
	s_add_u32 s10, s92, 0x3800
	s_addc_u32 s11, s93, 0
	s_mov_b32 s7, 0x400001
	v_mov_b32_e32 v2, 0
	s_branch .LBB0_51

.LBB0_70:
	s_waitcnt vmcnt(0) lgkmcnt(0)
	s_barrier
	s_mov_b64 s[0:1], exec
	v_readlane_b32 s6, v246, 2
	v_readlane_b32 s7, v246, 3
	s_and_b64 s[6:7], s[0:1], s[6:7]
	s_mov_b64 exec, s[6:7]
	s_cbranch_execz .Lsb1_arr_end
	s_lshl_b32 s8, s33, 8
	s_add_u32 s8, s8, 0x56000
	s_add_u32 s8, s92, s8
	s_addc_u32 s9, s93, 0
	v_mov_b32_e32 v2, 0
	v_mov_b32_e32 v3, 1
	global_atomic_add v3, v2, v3, s[8:9] sc0
	s_add_u32 s14, s92, 0x400
	s_addc_u32 s15, s93, 0
	s_mov_b64 s[16:17], exec
	s_mov_b32 s10, 0x400000
.Lsb1_census:
	s_mov_b64 exec, 0xffff
	v_mbcnt_lo_u32_b32 v5, -1, 0
	v_lshlrev_b32_e32 v5, 8, v5
	global_load_dword v4, v5, s[14:15] sc1
	s_waitcnt vmcnt(0)
	s_mov_b64 exec, s[16:17]
	v_readlane_b32 s11, v4, 0
	v_readlane_b32 s18, v4, 1
	s_add_u32 s11, s11, s18
	v_readlane_b32 s18, v4, 2
	s_add_u32 s11, s11, s18
	v_readlane_b32 s18, v4, 3
	s_add_u32 s11, s11, s18
	v_readlane_b32 s18, v4, 4
	s_add_u32 s11, s11, s18
	v_readlane_b32 s18, v4, 5
	s_add_u32 s11, s11, s18
	v_readlane_b32 s18, v4, 6
	s_add_u32 s11, s11, s18
	v_readlane_b32 s18, v4, 7
	s_add_u32 s11, s11, s18
	v_readlane_b32 s18, v4, 8
	s_add_u32 s11, s11, s18
	v_readlane_b32 s18, v4, 9
	s_add_u32 s11, s11, s18
	v_readlane_b32 s18, v4, 10
	s_add_u32 s11, s11, s18
	v_readlane_b32 s18, v4, 11
	s_add_u32 s11, s11, s18
	v_readlane_b32 s18, v4, 12
	s_add_u32 s11, s11, s18
	v_readlane_b32 s18, v4, 13
	s_add_u32 s11, s11, s18
	v_readlane_b32 s18, v4, 14
	s_add_u32 s11, s11, s18
	v_readlane_b32 s18, v4, 15
	s_add_u32 s11, s11, s18
	s_cmpk_eq_u32 s11, 0x100
	s_cbranch_scc1 .Lsb1_census_ok
	s_sleep 1
	s_sub_u32 s10, s10, 1
	s_cmp_lg_u32 s10, 0
	s_cbranch_scc1 .Lsb1_census
.Lsb1_census_ok:
	v_readlane_b32 s18, v4, s33
	v_readfirstlane_b32 s19, v3
	s_add_u32 s19, s19, 1
	s_cmp_lg_u32 s19, s18
	s_cbranch_scc1 .Lsb1_arr_end
	buffer_wbl2 sc1
	s_waitcnt vmcnt(0)
	s_add_u32 s8, s92, 0x57000
	s_addc_u32 s9, s93, 0
	v_mov_b32_e32 v3, s18
	global_atomic_add v2, v3, s[8:9]
.Lsb1_arr_end:
	s_mov_b64 exec, s[0:1]
	s_mov_b32 s100, 1
	s_lshl_b32 s4, s2, 3
	s_add_i32 s4, s96, s4
	s_lshl_b32 s6, s3, 3
	s_and_b32 s5, s97, 0xffffffc0
	v_readlane_b32 s8, v246, 0
	v_readlane_b32 s9, v246, 1
	s_sub_u32 s8, s8, 0xf0
	s_subb_u32 s9, s9, 0
	s_load_dwordx16 s[12:27], s[8:9], 0x80
	s_waitcnt lgkmcnt(0)
	s_branch .LBB0_13

.Lsb1_wait:
	s_waitcnt vmcnt(0) lgkmcnt(0)
	s_barrier
	s_mov_b64 s[0:1], exec
	v_readlane_b32 s6, v246, 2
	v_readlane_b32 s7, v246, 3
	s_and_b64 s[6:7], s[0:1], s[6:7]
	s_mov_b64 exec, s[6:7]
	s_cbranch_execz .Lsb1_w_end
	buffer_inv sc1
	s_add_u32 s8, s92, 0x57000
	s_addc_u32 s9, s93, 0
	v_mov_b32_e32 v2, 0
	s_mov_b32 s10, 0x400000
	s_movk_i32 s11, 0xff
.Lsb1_wpoll:
	global_load_dword v3, v2, s[8:9] sc1
	s_waitcnt vmcnt(0)
	v_cmp_lt_u32_e32 vcc, s11, v3
	s_cbranch_vccnz .Lsb1_w_end
	s_sleep 1
	s_sub_u32 s10, s10, 1
	s_cmp_lg_u32 s10, 0
	s_cbranch_scc1 .Lsb1_wpoll
.Lsb1_w_end:
	s_mov_b64 exec, s[0:1]
	s_barrier
	s_mov_b64 s[4:5], -1
